# final135
# speedup vs baseline: 1.0014x; 1.0014x over previous
; __device__ __forceinline__ int opaque_tid() { int t = threadIdx.x; asm volatile("" : "+v"(t)); return t; }
; __device__ void phase_attn(const Params& p, char* smem) {
;   const int tid = opaque_tid(), lane = tid & 63, w = tid >> 6;
;   const int l15 = lane & 15, lq = lane >> 4;
;   char* ws = p.ws;
;   const bf16_t* qk = (const bf16_t*)(ws + OFF_B);
;   const bf16_t* vT = (const bf16_t*)(ws + OFF_B_VT);
;   const bf16_t* bcx = (const bf16_t*)(ws + OFF_B_BCX);
;   bf16_t* mixed = (bf16_t*)(ws + OFF_A);
;   bf16_t* sP = (bf16_t*)smem + w * (32 * 72);
;   float* sSsq = (float*)(smem + 4 * 32 * 72 * 2);
;   float* sO = (float*)(smem + 20480) + w * 2048;
;   const float mk1 = (l15 & 1) ? 0.f : 1.f, mk2 = (l15 & 2) ? 0.f : 1.f, mk4 = (l15 & 4) ? 0.f : 1.f, mk8 = (l15 & 8) ? 0.f : 1.f;
;   const int cgrp = (gridDim.x >= 2) ? (int)(blockIdx.x & 1) : 0;
.LBB0_221:
	v_ashrrev_i32_e32 v9, 6, v22
	s_movk_i32 s4, 0x1200
	v_mul_lo_u32 v0, v9, s4
	s_movk_i32 s4, 0xe00
	v_mad_u64_u32 v[2:3], s[4:5], v9, s4, v[0:1]
	v_and_b32_e32 v1, 1, v22
	v_cmp_eq_u32_e32 vcc, 0, v1
	v_and_b32_e32 v1, 2, v22
	v_lshlrev_b32_e32 v128, 7, v9
	v_cndmask_b32_e64 v153, 0, 1.0, vcc
	v_cmp_eq_u32_e32 vcc, 0, v1
	v_and_b32_e32 v1, 4, v22
	v_mov_b32_e32 v132, 0
	v_and_b32_e32 v8, 63, v22
	v_and_b32_e32 v151, 15, v22
	v_cndmask_b32_e64 v155, 0, 1.0, vcc
	v_cmp_eq_u32_e32 vcc, 0, v1
	v_and_b32_e32 v1, 8, v22
	v_and_b32_e32 v130, 48, v22
	v_mov_b32_e32 v131, v132
	v_ashrrev_i32_e32 v129, 31, v128
	v_cndmask_b32_e64 v180, 0, 1.0, vcc
	v_cmp_eq_u32_e32 vcc, 0, v1
	v_lshl_add_u64 v[4:5], s[20:21], 0, v[130:131]
	v_lshlrev_b32_e32 v6, 1, v151
	v_mul_u32_u24_e32 v1, 0x90, v151
	v_lshl_or_b32 v184, v8, 2, v2
	v_mov_b32_e32 v7, v132
	v_lshlrev_b64 v[2:3], 1, v[128:129]
	v_bfe_u32 v10, v22, 4, 2
	v_or_b32_e32 v11, v0, v6
	v_add3_u32 v183, v0, v1, v130
	v_lshl_add_u64 v[0:1], s[12:13], 0, v[6:7]
	v_lshl_add_u64 v[136:137], v[4:5], 0, v[2:3]
	v_lshlrev_b32_e32 v4, 5, v8
	v_mov_b32_e32 v5, v132
	v_lshlrev_b32_e32 v182, 2, v10
	v_mul_u32_u24_e32 v6, 0x240, v10
	v_lshl_add_u64 v[138:139], s[24:25], 0, v[4:5]
	s_mov_b64 s[6:7], 0x1000
	v_lshl_add_u64 v[4:5], s[20:21], 0, v[2:3]
	v_lshl_add_u64 v[144:145], v[0:1], 0, v[2:3]
	v_mbcnt_lo_u32_b32 v0, -1, 0
	s_mov_b32 s37, 0
	v_cndmask_b32_e64 v181, 0, 1.0, vcc
	v_lshl_add_u64 v[134:135], s[14:15], 0, v[130:131]
	v_cmp_eq_u32_e64 s[4:5], 0, v151
	v_lshlrev_b32_e32 v185, 3, v9
	v_or_b32_e32 v186, 64, v128
	v_or_b32_e32 v187, 1, v182
	v_or_b32_e32 v188, 2, v182
	v_or_b32_e32 v189, 3, v182
	v_or_b32_e32 v190, 16, v182
	v_or_b32_e32 v191, 17, v182
	v_or_b32_e32 v194, 18, v182
	v_or_b32_e32 v195, 19, v182
	v_lshl_add_u64 v[140:141], v[138:139], 0, s[6:7]
	v_lshl_add_u64 v[142:143], v[4:5], 0, v[130:131]
	s_lshl_b32 s25, s2, 5
	s_lshl_b32 s39, s34, 5
	v_lshlrev_b32_e32 v146, 4, v8
	v_mov_b32_e32 v147, v132
	s_mov_b32 s24, 0x3e38aa3b
	s_mov_b32 s41, 0xbe38aa3b
	v_add_u32_e32 v196, v11, v6
	s_mov_b32 s46, 0xc3070000
	s_mov_b32 s38, 0x3b000000
	s_mov_b32 s40, 0x358637bd
	s_mov_b32 s47, 0x800000
	s_movk_i32 s52, 0x7fff
	s_movk_i32 s53, 0xc00
	s_mov_b32 s65, 0xb7a0000
	v_mov_b32_e32 v198, 0x358637bd
	s_mov_b64 s[42:43], 0xc00
	s_mov_b64 s[44:45], 0x800
	v_mbcnt_hi_u32_b32 v199, -1, v0
	v_mov_b32_e32 v200, 1
	s_mov_b32 s66, s2
	s_branch .LBB0_223
